# v113 + seam 0 issues its L1 invalidate at arrival instead of after the release
# baseline (speedup 1.0000x reference)
; __device__ __forceinline__ unsigned xb_ld(unsigned* p)              { return __hip_atomic_load(p, __ATOMIC_RELAXED, __HIP_MEMORY_SCOPE_AGENT); }
; __device__ __forceinline__ unsigned xb_add(unsigned* p, unsigned v) { return __hip_atomic_fetch_add(p, v, __ATOMIC_RELAXED, __HIP_MEMORY_SCOPE_AGENT); }
; #define XB_SPIN(cond, bar) do { unsigned _sp = 0; while (cond) { __builtin_amdgcn_s_sleep(1); \
;     if ((++_sp & 255u) == 0u) { if (xb_ld(&(bar)[XB_TMO])) break; if (_sp > XB_SPIN_CAP) { atomicAdd(&(bar)[XB_TMO], 1u); break; } } } } while (0)
; #define SEAM(k) do { if (IN(k) && IN((k) + 1)) { xcd_barrier(bar, wave == 0 && mk_lane() == 0); } } while (0)
; __device__ __forceinline__ void xcd_barrier(const XcdBarrier& b, bool leader) {
;     asm volatile("s_waitcnt vmcnt(0)" ::: "memory");
;     __syncthreads();
;     if (leader) {
;         unsigned* bar = b.bar;
;         __builtin_amdgcn_s_waitcnt(0);
;         unsigned nloc = b.st[0], nx = b.st[1];
;         if (nloc == 0u) { xcd_barrier_complete(bar, b.x, nloc, nx); b.st[0] = nloc; b.st[1] = nx; }
;         const unsigned old = xb_add(&bar[XB_XSUB(b.x)], 1u);
;         const unsigned gen = old / nloc;
;         if (old + 1u == (gen + 1u) * nloc) {
;             __builtin_amdgcn_fence(__ATOMIC_RELEASE, "agent");
;             asm volatile("s_waitcnt vmcnt(0)" ::: "memory");
;             const unsigned og = xb_add(&bar[XB_TOP], 1u);
;             const unsigned tg = og / nx;
;             if (og + 1u == (tg + 1u) * nx) xb_add(&bar[XB_TOPGEN], 1u);
;             else XB_SPIN(xb_ld(&bar[XB_TOPGEN]) == tg, bar);
;             __builtin_amdgcn_fence(__ATOMIC_ACQUIRE, "agent");
;             xb_add(&bar[XB_XGEN(b.x)], 1u);
;             asm volatile("s_waitcnt vmcnt(0)" ::: "memory");
;         } else {
;             XB_SPIN(xb_ld(&bar[XB_XGEN(b.x)]) == gen, bar);
; __global__ void __launch_bounds__(NWAVES * 64, 2) mk_fwd(Params P) {
;     ...
;         __syncthreads();
;     }
;     SEAM(0);
.LBB0_178:
	s_lshl_b32 s2, s92, 8
	v_readlane_b32 s6, v254, 2
	v_readlane_b32 s7, v254, 3
	s_add_u32 s6, s6, s2
	s_addc_u32 s7, s7, 0
	v_mov_b32_e32 v1, 0x1000
	v_mov_b32_e32 v3, 1
	v_sub_u32_e32 v4, 0, v2
	global_atomic_add v3, v1, v3, s[6:7] offset:1024 sc0
	buffer_inv sc1
	v_cvt_f32_u32_e32 v1, v2
	v_rcp_iflag_f32_e32 v1, v1
	s_nop 0
	v_mul_f32_e32 v1, 0x4f7ffffe, v1
	v_cvt_u32_f32_e32 v1, v1
	v_mul_lo_u32 v4, v4, v1
	v_mul_hi_u32 v4, v1, v4
	v_add_u32_e32 v1, v1, v4
	s_waitcnt vmcnt(1)
	v_mul_hi_u32 v1, v3, v1
	v_mul_lo_u32 v4, v1, v2
	v_sub_u32_e32 v4, v3, v4
	v_add_u32_e32 v5, 1, v1
	v_cmp_ge_u32_e32 vcc, v4, v2
	v_add_u32_e32 v3, 1, v3
	s_nop 0
	v_cndmask_b32_e32 v1, v1, v5, vcc
	v_sub_u32_e32 v5, v4, v2
	v_cndmask_b32_e32 v4, v4, v5, vcc
	v_add_u32_e32 v5, 1, v1
	v_cmp_ge_u32_e32 vcc, v4, v2
	s_nop 1
	v_cndmask_b32_e32 v1, v1, v5, vcc
	v_mul_lo_u32 v4, v2, v1
	v_add_u32_e32 v2, v4, v2
	v_cmp_ne_u32_e32 vcc, v3, v2
	s_and_saveexec_b64 s[2:3], vcc
	s_xor_b64 s[8:9], exec, s[2:3]
	s_cbranch_execz .LBB0_192
	s_waitcnt lgkmcnt(0)
	v_mov_b32_e32 v0, 0x2000
	global_load_dword v0, v0, s[6:7] offset:1024 sc1
	s_add_u32 s14, s6, 0x2400
	s_addc_u32 s15, s7, 0
	s_waitcnt vmcnt(0)
	v_cmp_eq_u32_e32 vcc, v0, v1
	s_and_saveexec_b64 s[10:11], vcc
	s_cbranch_execz .LBB0_191
	s_add_u32 s12, s72, 0x310200
	s_addc_u32 s13, s73, 0
	s_mov_b32 s2, 1
	s_mov_b64 s[18:19], 0
	v_mov_b32_e32 v0, 0
	s_branch .LBB0_182

; __device__ __forceinline__ unsigned xb_ld(unsigned* p)              { return __hip_atomic_load(p, __ATOMIC_RELAXED, __HIP_MEMORY_SCOPE_AGENT); }
; #define XB_SPIN(cond, bar) do { unsigned _sp = 0; while (cond) { __builtin_amdgcn_s_sleep(1); \
;     if ((++_sp & 255u) == 0u) { if (xb_ld(&(bar)[XB_TMO])) break; if (_sp > XB_SPIN_CAP) { atomicAdd(&(bar)[XB_TMO], 1u); break; } } } } while (0)
; __device__ __forceinline__ void xcd_barrier(const XcdBarrier& b, bool leader) {
;     ...
;             XB_SPIN(xb_ld(&bar[XB_XGEN(b.x)]) == gen, bar);
;             __builtin_amdgcn_fence(__ATOMIC_ACQUIRE, "agent");
;             asm volatile("s_waitcnt vmcnt(0)" ::: "memory");
.LBB0_191:
	s_or_b64 exec, exec, s[10:11]
	s_waitcnt vmcnt(0)
	s_waitcnt vmcnt(0)

; __device__ __forceinline__ unsigned xb_ld(unsigned* p)              { return __hip_atomic_load(p, __ATOMIC_RELAXED, __HIP_MEMORY_SCOPE_AGENT); }
; __device__ __forceinline__ unsigned xb_add(unsigned* p, unsigned v) { return __hip_atomic_fetch_add(p, v, __ATOMIC_RELAXED, __HIP_MEMORY_SCOPE_AGENT); }
; #define XB_SPIN(cond, bar) do { unsigned _sp = 0; while (cond) { __builtin_amdgcn_s_sleep(1); \
;     if ((++_sp & 255u) == 0u) { if (xb_ld(&(bar)[XB_TMO])) break; if (_sp > XB_SPIN_CAP) { atomicAdd(&(bar)[XB_TMO], 1u); break; } } } } while (0)
; __device__ __forceinline__ void xcd_barrier(const XcdBarrier& b, bool leader) {
;     ...
;             if (og + 1u == (tg + 1u) * nx) xb_add(&bar[XB_TOPGEN], 1u);
;             else XB_SPIN(xb_ld(&bar[XB_TOPGEN]) == tg, bar);
;             __builtin_amdgcn_fence(__ATOMIC_ACQUIRE, "agent");
;             xb_add(&bar[XB_XGEN(b.x)], 1u);
;             asm volatile("s_waitcnt vmcnt(0)" ::: "memory");
.LBB0_209:
	s_or_b64 exec, exec, s[8:9]
	v_mov_b32_e32 v0, 0x2000
	v_mov_b32_e32 v1, 1
	s_waitcnt vmcnt(0)
	global_atomic_add v0, v1, s[6:7] offset:1024
	s_waitcnt vmcnt(0)
